# UP GEMM epilogue staged through LDS (SA(1,1) + 16 KB static LDS): full 512-B row stores instead of 16x64-B fragment stores
# speedup vs baseline: 1.0051x; 1.0051x over previous
.LBB0_613:
	s_and_b64 vcc, exec, s[12:13]
	s_cbranch_vccz .LBB0_615
	v_mbcnt_lo_u32_b32 v217, -1, 0
	v_mbcnt_hi_u32_b32 v217, -1, v217
	v_readfirstlane_b32 s100, v240
	v_lshrrev_b32_e32 v216, 3, v240
	v_and_b32_e32 v218, 7, v239
	v_xor_b32_e32 v216, v216, v218
	v_lshlrev_b32_e32 v216, 4, v216
	v_lshl_add_u32 v216, v239, 9, v216
	s_lshl_b32 s101, s16, 7
	s_add_i32 s101, s101, 0xc000
	v_add_u32_e32 v206, s101, v216
	v_add_u32_e32 v207, 0x14400, v206
	v_lshrrev_b32_e32 v218, 5, v217
	v_and_b32_e32 v219, 31, v217
	s_lshr_b32 s101, s100, 3
	s_lshr_b32 s100, s16, 2
	s_add_i32 s100, s100, s101
	v_add_u32_e32 v216, s100, v218
	v_and_b32_e32 v166, 7, v216
	v_xor_b32_e32 v166, v166, v219
	v_lshlrev_b32_e32 v166, 4, v166
	v_lshl_add_u32 v208, v216, 9, v166
	v_add_u32_e32 v167, 2, v216
	v_and_b32_e32 v166, 7, v167
	v_xor_b32_e32 v166, v166, v219
	v_lshlrev_b32_e32 v166, 4, v166
	v_lshl_add_u32 v209, v167, 9, v166
	v_add_u32_e32 v210, 0x20400, v208
	v_add_u32_e32 v211, 0x20400, v209
	v_add_u32_e32 v208, 0xc000, v208
	v_add_u32_e32 v209, 0xc000, v209
	s_add_i32 s101, s101, s43
	v_add_u32_e32 v212, s101, v218
	v_mov_b32_e32 v213, 0
	v_lshlrev_b32_e32 v214, 4, v219
	s_lshl_b32 s101, s42, 1
	v_add_u32_e32 v214, s101, v214
	v_mov_b32_e32 v215, 0
	v_lshlrev_b64 v[212:213], 13, v[212:213]
	v_lshl_add_u64 v[212:213], v[212:213], 0, v[214:215]
	v_lshl_add_u64 v[212:213], s[22:23], 0, v[212:213]
	s_mov_b64 s[100:101], 0x4000
	v_lshl_add_u64 v[214:215], v[212:213], 0, s[100:101]
	v_pk_fma_f32 v[172:173], v[104:105], v[160:161], v[140:141] op_sel_hi:[1,0,1]
	v_pk_fma_f32 v[174:175], v[106:107], v[160:161], v[142:143] op_sel_hi:[1,0,1]
	v_pk_fma_f32 v[176:177], v[96:97], v[160:161], v[136:137] op_sel_hi:[1,0,1]
	v_pk_fma_f32 v[178:179], v[98:99], v[160:161], v[138:139] op_sel_hi:[1,0,1]
	v_pk_fma_f32 v[180:181], v[44:45], v[160:161], v[132:133] op_sel_hi:[1,0,1]
	v_pk_fma_f32 v[182:183], v[46:47], v[160:161], v[134:135] op_sel_hi:[1,0,1]
	v_pk_fma_f32 v[184:185], v[40:41], v[160:161], v[128:129] op_sel_hi:[1,0,1]
	v_pk_fma_f32 v[186:187], v[42:43], v[160:161], v[130:131] op_sel_hi:[1,0,1]
	v_max_f32_e32 v172, 0, v172
	v_max_f32_e32 v173, 0, v173
	v_max_f32_e32 v174, 0, v174
	v_max_f32_e32 v175, 0, v175
	v_max_f32_e32 v176, 0, v176
	v_max_f32_e32 v177, 0, v177
	v_max_f32_e32 v178, 0, v178
	v_max_f32_e32 v179, 0, v179
	v_max_f32_e32 v180, 0, v180
	v_max_f32_e32 v181, 0, v181
	v_max_f32_e32 v182, 0, v182
	v_max_f32_e32 v183, 0, v183
	v_max_f32_e32 v184, 0, v184
	v_max_f32_e32 v185, 0, v185
	v_max_f32_e32 v186, 0, v186
	v_max_f32_e32 v187, 0, v187
	v_pk_mul_f32 v[172:173], v[172:173], v[172:173]
	v_pk_mul_f32 v[174:175], v[174:175], v[174:175]
	v_pk_mul_f32 v[176:177], v[176:177], v[176:177]
	v_pk_mul_f32 v[178:179], v[178:179], v[178:179]
	v_pk_mul_f32 v[180:181], v[180:181], v[180:181]
	v_pk_mul_f32 v[182:183], v[182:183], v[182:183]
	v_pk_mul_f32 v[184:185], v[184:185], v[184:185]
	v_pk_mul_f32 v[186:187], v[186:187], v[186:187]
	v_cvt_pk_bf16_f32 v172, v172, v173
	v_cvt_pk_bf16_f32 v180, v180, v181
	v_cvt_pk_bf16_f32 v173, v174, v175
	v_cvt_pk_bf16_f32 v181, v182, v183
	v_cvt_pk_bf16_f32 v174, v176, v177
	v_cvt_pk_bf16_f32 v182, v184, v185
	v_cvt_pk_bf16_f32 v175, v178, v179
	v_cvt_pk_bf16_f32 v183, v186, v187
	ds_write_b128 v206, v[172:175]
	ds_write_b128 v206, v[180:183] offset:256
	s_waitcnt lgkmcnt(0)
	s_barrier
	ds_read_b128 v[162:165], v208
	ds_read_b128 v[188:191], v209
	v_pk_fma_f32 v[172:173], v[88:89], v[158:159], v[140:141] op_sel_hi:[1,0,1]
	v_pk_fma_f32 v[174:175], v[90:91], v[158:159], v[142:143] op_sel_hi:[1,0,1]
	v_pk_fma_f32 v[176:177], v[80:81], v[158:159], v[136:137] op_sel_hi:[1,0,1]
	v_pk_fma_f32 v[178:179], v[82:83], v[158:159], v[138:139] op_sel_hi:[1,0,1]
	v_pk_fma_f32 v[180:181], v[36:37], v[158:159], v[132:133] op_sel_hi:[1,0,1]
	v_pk_fma_f32 v[182:183], v[38:39], v[158:159], v[134:135] op_sel_hi:[1,0,1]
	v_pk_fma_f32 v[184:185], v[32:33], v[158:159], v[128:129] op_sel_hi:[1,0,1]
	v_pk_fma_f32 v[186:187], v[34:35], v[158:159], v[130:131] op_sel_hi:[1,0,1]
	v_max_f32_e32 v172, 0, v172
	v_max_f32_e32 v173, 0, v173
	v_max_f32_e32 v174, 0, v174
	v_max_f32_e32 v175, 0, v175
	v_max_f32_e32 v176, 0, v176
	v_max_f32_e32 v177, 0, v177
	v_max_f32_e32 v178, 0, v178
	v_max_f32_e32 v179, 0, v179
	v_max_f32_e32 v180, 0, v180
	v_max_f32_e32 v181, 0, v181
	v_max_f32_e32 v182, 0, v182
	v_max_f32_e32 v183, 0, v183
	v_max_f32_e32 v184, 0, v184
	v_max_f32_e32 v185, 0, v185
	v_max_f32_e32 v186, 0, v186
	v_max_f32_e32 v187, 0, v187
	v_pk_mul_f32 v[172:173], v[172:173], v[172:173]
	v_pk_mul_f32 v[174:175], v[174:175], v[174:175]
	v_pk_mul_f32 v[176:177], v[176:177], v[176:177]
	v_pk_mul_f32 v[178:179], v[178:179], v[178:179]
	v_pk_mul_f32 v[180:181], v[180:181], v[180:181]
	v_pk_mul_f32 v[182:183], v[182:183], v[182:183]
	v_pk_mul_f32 v[184:185], v[184:185], v[184:185]
	v_pk_mul_f32 v[186:187], v[186:187], v[186:187]
	v_cvt_pk_bf16_f32 v172, v172, v173
	v_cvt_pk_bf16_f32 v180, v180, v181
	v_cvt_pk_bf16_f32 v173, v174, v175
	v_cvt_pk_bf16_f32 v181, v182, v183
	v_cvt_pk_bf16_f32 v174, v176, v177
	v_cvt_pk_bf16_f32 v182, v184, v185
	v_cvt_pk_bf16_f32 v175, v178, v179
	v_cvt_pk_bf16_f32 v183, v186, v187
	s_waitcnt lgkmcnt(0)
	global_store_dwordx4 v[212:213], v[162:165], off
	global_store_dwordx4 v[214:215], v[188:191], off
	s_mov_b64 s[100:101], 0x20000
	ds_write_b128 v207, v[172:175]
	ds_write_b128 v207, v[180:183] offset:256
	v_lshl_add_u64 v[212:213], v[212:213], 0, s[100:101]
	v_lshl_add_u64 v[214:215], v[214:215], 0, s[100:101]
	s_waitcnt lgkmcnt(0)
	s_barrier
	ds_read_b128 v[162:165], v210
	ds_read_b128 v[188:191], v211
	v_pk_fma_f32 v[172:173], v[72:73], v[156:157], v[140:141] op_sel_hi:[1,0,1]
	v_pk_fma_f32 v[174:175], v[74:75], v[156:157], v[142:143] op_sel_hi:[1,0,1]
	v_pk_fma_f32 v[176:177], v[64:65], v[156:157], v[136:137] op_sel_hi:[1,0,1]
	v_pk_fma_f32 v[178:179], v[66:67], v[156:157], v[138:139] op_sel_hi:[1,0,1]
	v_pk_fma_f32 v[180:181], v[28:29], v[156:157], v[132:133] op_sel_hi:[1,0,1]
	v_pk_fma_f32 v[182:183], v[30:31], v[156:157], v[134:135] op_sel_hi:[1,0,1]
	v_pk_fma_f32 v[184:185], v[24:25], v[156:157], v[128:129] op_sel_hi:[1,0,1]
	v_pk_fma_f32 v[186:187], v[26:27], v[156:157], v[130:131] op_sel_hi:[1,0,1]
	v_max_f32_e32 v172, 0, v172
	v_max_f32_e32 v173, 0, v173
	v_max_f32_e32 v174, 0, v174
	v_max_f32_e32 v175, 0, v175
	v_max_f32_e32 v176, 0, v176
	v_max_f32_e32 v177, 0, v177
	v_max_f32_e32 v178, 0, v178
	v_max_f32_e32 v179, 0, v179
	v_max_f32_e32 v180, 0, v180
	v_max_f32_e32 v181, 0, v181
	v_max_f32_e32 v182, 0, v182
	v_max_f32_e32 v183, 0, v183
	v_max_f32_e32 v184, 0, v184
	v_max_f32_e32 v185, 0, v185
	v_max_f32_e32 v186, 0, v186
	v_max_f32_e32 v187, 0, v187
	v_pk_mul_f32 v[172:173], v[172:173], v[172:173]
	v_pk_mul_f32 v[174:175], v[174:175], v[174:175]
	v_pk_mul_f32 v[176:177], v[176:177], v[176:177]
	v_pk_mul_f32 v[178:179], v[178:179], v[178:179]
	v_pk_mul_f32 v[180:181], v[180:181], v[180:181]
	v_pk_mul_f32 v[182:183], v[182:183], v[182:183]
	v_pk_mul_f32 v[184:185], v[184:185], v[184:185]
	v_pk_mul_f32 v[186:187], v[186:187], v[186:187]
	v_cvt_pk_bf16_f32 v172, v172, v173
	v_cvt_pk_bf16_f32 v180, v180, v181
	v_cvt_pk_bf16_f32 v173, v174, v175
	v_cvt_pk_bf16_f32 v181, v182, v183
	v_cvt_pk_bf16_f32 v174, v176, v177
	v_cvt_pk_bf16_f32 v182, v184, v185
	v_cvt_pk_bf16_f32 v175, v178, v179
	v_cvt_pk_bf16_f32 v183, v186, v187
	s_waitcnt lgkmcnt(0)
	global_store_dwordx4 v[212:213], v[162:165], off
	global_store_dwordx4 v[214:215], v[188:191], off
	s_mov_b64 s[100:101], 0x20000
	ds_write_b128 v206, v[172:175]
	ds_write_b128 v206, v[180:183] offset:256
	v_lshl_add_u64 v[212:213], v[212:213], 0, s[100:101]
	v_lshl_add_u64 v[214:215], v[214:215], 0, s[100:101]
	s_waitcnt lgkmcnt(0)
	s_barrier
	ds_read_b128 v[162:165], v208
	ds_read_b128 v[188:191], v209
	v_pk_fma_f32 v[172:173], v[56:57], v[154:155], v[140:141] op_sel_hi:[1,0,1]
	v_pk_fma_f32 v[174:175], v[58:59], v[154:155], v[142:143] op_sel_hi:[1,0,1]
	v_pk_fma_f32 v[176:177], v[48:49], v[154:155], v[136:137] op_sel_hi:[1,0,1]
	v_pk_fma_f32 v[178:179], v[50:51], v[154:155], v[138:139] op_sel_hi:[1,0,1]
	v_pk_fma_f32 v[180:181], v[20:21], v[154:155], v[132:133] op_sel_hi:[1,0,1]
	v_pk_fma_f32 v[182:183], v[22:23], v[154:155], v[134:135] op_sel_hi:[1,0,1]
	v_pk_fma_f32 v[184:185], v[16:17], v[154:155], v[128:129] op_sel_hi:[1,0,1]
	v_pk_fma_f32 v[186:187], v[18:19], v[154:155], v[130:131] op_sel_hi:[1,0,1]
	v_max_f32_e32 v172, 0, v172
	v_max_f32_e32 v173, 0, v173
	v_max_f32_e32 v174, 0, v174
	v_max_f32_e32 v175, 0, v175
	v_max_f32_e32 v176, 0, v176
	v_max_f32_e32 v177, 0, v177
	v_max_f32_e32 v178, 0, v178
	v_max_f32_e32 v179, 0, v179
	v_max_f32_e32 v180, 0, v180
	v_max_f32_e32 v181, 0, v181
	v_max_f32_e32 v182, 0, v182
	v_max_f32_e32 v183, 0, v183
	v_max_f32_e32 v184, 0, v184
	v_max_f32_e32 v185, 0, v185
	v_max_f32_e32 v186, 0, v186
	v_max_f32_e32 v187, 0, v187
	v_pk_mul_f32 v[172:173], v[172:173], v[172:173]
	v_pk_mul_f32 v[174:175], v[174:175], v[174:175]
	v_pk_mul_f32 v[176:177], v[176:177], v[176:177]
	v_pk_mul_f32 v[178:179], v[178:179], v[178:179]
	v_pk_mul_f32 v[180:181], v[180:181], v[180:181]
	v_pk_mul_f32 v[182:183], v[182:183], v[182:183]
	v_pk_mul_f32 v[184:185], v[184:185], v[184:185]
	v_pk_mul_f32 v[186:187], v[186:187], v[186:187]
	v_cvt_pk_bf16_f32 v172, v172, v173
	v_cvt_pk_bf16_f32 v180, v180, v181
	v_cvt_pk_bf16_f32 v173, v174, v175
	v_cvt_pk_bf16_f32 v181, v182, v183
	v_cvt_pk_bf16_f32 v174, v176, v177
	v_cvt_pk_bf16_f32 v182, v184, v185
	v_cvt_pk_bf16_f32 v175, v178, v179
	v_cvt_pk_bf16_f32 v183, v186, v187
	s_waitcnt lgkmcnt(0)
	global_store_dwordx4 v[212:213], v[162:165], off
	global_store_dwordx4 v[214:215], v[188:191], off
	s_mov_b64 s[100:101], 0x20000
	ds_write_b128 v207, v[172:175]
	ds_write_b128 v207, v[180:183] offset:256
	v_lshl_add_u64 v[212:213], v[212:213], 0, s[100:101]
	v_lshl_add_u64 v[214:215], v[214:215], 0, s[100:101]
	s_waitcnt lgkmcnt(0)
	s_barrier
	ds_read_b128 v[162:165], v210
	ds_read_b128 v[188:191], v211
	v_pk_fma_f32 v[172:173], v[12:13], v[150:151], v[140:141] op_sel_hi:[1,0,1]
	v_pk_fma_f32 v[174:175], v[14:15], v[150:151], v[142:143] op_sel_hi:[1,0,1]
	v_pk_fma_f32 v[176:177], v[8:9], v[150:151], v[136:137] op_sel_hi:[1,0,1]
	v_pk_fma_f32 v[178:179], v[10:11], v[150:151], v[138:139] op_sel_hi:[1,0,1]
	v_pk_fma_f32 v[180:181], v[84:85], v[150:151], v[132:133] op_sel_hi:[1,0,1]
	v_pk_fma_f32 v[182:183], v[86:87], v[150:151], v[134:135] op_sel_hi:[1,0,1]
	v_pk_fma_f32 v[184:185], v[92:93], v[150:151], v[128:129] op_sel_hi:[1,0,1]
	v_pk_fma_f32 v[186:187], v[94:95], v[150:151], v[130:131] op_sel_hi:[1,0,1]
	v_max_f32_e32 v172, 0, v172
	v_max_f32_e32 v173, 0, v173
	v_max_f32_e32 v174, 0, v174
	v_max_f32_e32 v175, 0, v175
	v_max_f32_e32 v176, 0, v176
	v_max_f32_e32 v177, 0, v177
	v_max_f32_e32 v178, 0, v178
	v_max_f32_e32 v179, 0, v179
	v_max_f32_e32 v180, 0, v180
	v_max_f32_e32 v181, 0, v181
	v_max_f32_e32 v182, 0, v182
	v_max_f32_e32 v183, 0, v183
	v_max_f32_e32 v184, 0, v184
	v_max_f32_e32 v185, 0, v185
	v_max_f32_e32 v186, 0, v186
	v_max_f32_e32 v187, 0, v187
	v_pk_mul_f32 v[172:173], v[172:173], v[172:173]
	v_pk_mul_f32 v[174:175], v[174:175], v[174:175]
	v_pk_mul_f32 v[176:177], v[176:177], v[176:177]
	v_pk_mul_f32 v[178:179], v[178:179], v[178:179]
	v_pk_mul_f32 v[180:181], v[180:181], v[180:181]
	v_pk_mul_f32 v[182:183], v[182:183], v[182:183]
	v_pk_mul_f32 v[184:185], v[184:185], v[184:185]
	v_pk_mul_f32 v[186:187], v[186:187], v[186:187]
	v_cvt_pk_bf16_f32 v172, v172, v173
	v_cvt_pk_bf16_f32 v180, v180, v181
	v_cvt_pk_bf16_f32 v173, v174, v175
	v_cvt_pk_bf16_f32 v181, v182, v183
	v_cvt_pk_bf16_f32 v174, v176, v177
	v_cvt_pk_bf16_f32 v182, v184, v185
	v_cvt_pk_bf16_f32 v175, v178, v179
	v_cvt_pk_bf16_f32 v183, v186, v187
	s_waitcnt lgkmcnt(0)
	global_store_dwordx4 v[212:213], v[162:165], off
	global_store_dwordx4 v[214:215], v[188:191], off
	s_mov_b64 s[100:101], 0xa0000
	ds_write_b128 v206, v[172:175]
	ds_write_b128 v206, v[180:183] offset:256
	v_lshl_add_u64 v[212:213], v[212:213], 0, s[100:101]
	v_lshl_add_u64 v[214:215], v[214:215], 0, s[100:101]
	s_waitcnt lgkmcnt(0)
	s_barrier
	ds_read_b128 v[162:165], v208
	ds_read_b128 v[188:191], v209
	v_pk_fma_f32 v[172:173], v[4:5], v[148:149], v[140:141] op_sel_hi:[1,0,1]
	v_pk_fma_f32 v[174:175], v[6:7], v[148:149], v[142:143] op_sel_hi:[1,0,1]
	v_pk_fma_f32 v[176:177], v[0:1], v[148:149], v[136:137] op_sel_hi:[1,0,1]
	v_pk_fma_f32 v[178:179], v[2:3], v[148:149], v[138:139] op_sel_hi:[1,0,1]
	v_pk_fma_f32 v[180:181], v[100:101], v[148:149], v[132:133] op_sel_hi:[1,0,1]
	v_pk_fma_f32 v[182:183], v[102:103], v[148:149], v[134:135] op_sel_hi:[1,0,1]
	v_pk_fma_f32 v[184:185], v[108:109], v[148:149], v[128:129] op_sel_hi:[1,0,1]
	v_pk_fma_f32 v[186:187], v[110:111], v[148:149], v[130:131] op_sel_hi:[1,0,1]
	v_max_f32_e32 v172, 0, v172
	v_max_f32_e32 v173, 0, v173
	v_max_f32_e32 v174, 0, v174
	v_max_f32_e32 v175, 0, v175
	v_max_f32_e32 v176, 0, v176
	v_max_f32_e32 v177, 0, v177
	v_max_f32_e32 v178, 0, v178
	v_max_f32_e32 v179, 0, v179
	v_max_f32_e32 v180, 0, v180
	v_max_f32_e32 v181, 0, v181
	v_max_f32_e32 v182, 0, v182
	v_max_f32_e32 v183, 0, v183
	v_max_f32_e32 v184, 0, v184
	v_max_f32_e32 v185, 0, v185
	v_max_f32_e32 v186, 0, v186
	v_max_f32_e32 v187, 0, v187
	v_pk_mul_f32 v[172:173], v[172:173], v[172:173]
	v_pk_mul_f32 v[174:175], v[174:175], v[174:175]
	v_pk_mul_f32 v[176:177], v[176:177], v[176:177]
	v_pk_mul_f32 v[178:179], v[178:179], v[178:179]
	v_pk_mul_f32 v[180:181], v[180:181], v[180:181]
	v_pk_mul_f32 v[182:183], v[182:183], v[182:183]
	v_pk_mul_f32 v[184:185], v[184:185], v[184:185]
	v_pk_mul_f32 v[186:187], v[186:187], v[186:187]
	v_cvt_pk_bf16_f32 v172, v172, v173
	v_cvt_pk_bf16_f32 v180, v180, v181
	v_cvt_pk_bf16_f32 v173, v174, v175
	v_cvt_pk_bf16_f32 v181, v182, v183
	v_cvt_pk_bf16_f32 v174, v176, v177
	v_cvt_pk_bf16_f32 v182, v184, v185
	v_cvt_pk_bf16_f32 v175, v178, v179
	v_cvt_pk_bf16_f32 v183, v186, v187
	s_waitcnt lgkmcnt(0)
	global_store_dwordx4 v[212:213], v[162:165], off
	global_store_dwordx4 v[214:215], v[188:191], off
	s_mov_b64 s[100:101], 0x20000
	ds_write_b128 v207, v[172:175]
	ds_write_b128 v207, v[180:183] offset:256
	v_lshl_add_u64 v[212:213], v[212:213], 0, s[100:101]
	v_lshl_add_u64 v[214:215], v[214:215], 0, s[100:101]
	s_waitcnt lgkmcnt(0)
	s_barrier
	ds_read_b128 v[162:165], v210
	ds_read_b128 v[188:191], v211
	v_pk_fma_f32 v[172:173], v[52:53], v[146:147], v[140:141] op_sel_hi:[1,0,1]
	v_pk_fma_f32 v[174:175], v[54:55], v[146:147], v[142:143] op_sel_hi:[1,0,1]
	v_pk_fma_f32 v[176:177], v[60:61], v[146:147], v[136:137] op_sel_hi:[1,0,1]
	v_pk_fma_f32 v[178:179], v[62:63], v[146:147], v[138:139] op_sel_hi:[1,0,1]
	v_pk_fma_f32 v[180:181], v[112:113], v[146:147], v[132:133] op_sel_hi:[1,0,1]
	v_pk_fma_f32 v[182:183], v[114:115], v[146:147], v[134:135] op_sel_hi:[1,0,1]
	v_pk_fma_f32 v[184:185], v[116:117], v[146:147], v[128:129] op_sel_hi:[1,0,1]
	v_pk_fma_f32 v[186:187], v[118:119], v[146:147], v[130:131] op_sel_hi:[1,0,1]
	v_max_f32_e32 v172, 0, v172
	v_max_f32_e32 v173, 0, v173
	v_max_f32_e32 v174, 0, v174
	v_max_f32_e32 v175, 0, v175
	v_max_f32_e32 v176, 0, v176
	v_max_f32_e32 v177, 0, v177
	v_max_f32_e32 v178, 0, v178
	v_max_f32_e32 v179, 0, v179
	v_max_f32_e32 v180, 0, v180
	v_max_f32_e32 v181, 0, v181
	v_max_f32_e32 v182, 0, v182
	v_max_f32_e32 v183, 0, v183
	v_max_f32_e32 v184, 0, v184
	v_max_f32_e32 v185, 0, v185
	v_max_f32_e32 v186, 0, v186
	v_max_f32_e32 v187, 0, v187
	v_pk_mul_f32 v[172:173], v[172:173], v[172:173]
	v_pk_mul_f32 v[174:175], v[174:175], v[174:175]
	v_pk_mul_f32 v[176:177], v[176:177], v[176:177]
	v_pk_mul_f32 v[178:179], v[178:179], v[178:179]
	v_pk_mul_f32 v[180:181], v[180:181], v[180:181]
	v_pk_mul_f32 v[182:183], v[182:183], v[182:183]
	v_pk_mul_f32 v[184:185], v[184:185], v[184:185]
	v_pk_mul_f32 v[186:187], v[186:187], v[186:187]
	v_cvt_pk_bf16_f32 v172, v172, v173
	v_cvt_pk_bf16_f32 v180, v180, v181
	v_cvt_pk_bf16_f32 v173, v174, v175
	v_cvt_pk_bf16_f32 v181, v182, v183
	v_cvt_pk_bf16_f32 v174, v176, v177
	v_cvt_pk_bf16_f32 v182, v184, v185
	v_cvt_pk_bf16_f32 v175, v178, v179
	v_cvt_pk_bf16_f32 v183, v186, v187
	s_waitcnt lgkmcnt(0)
	global_store_dwordx4 v[212:213], v[162:165], off
	global_store_dwordx4 v[214:215], v[188:191], off
	s_mov_b64 s[100:101], 0x20000
	ds_write_b128 v206, v[172:175]
	ds_write_b128 v206, v[180:183] offset:256
	v_lshl_add_u64 v[212:213], v[212:213], 0, s[100:101]
	v_lshl_add_u64 v[214:215], v[214:215], 0, s[100:101]
	s_waitcnt lgkmcnt(0)
	s_barrier
	ds_read_b128 v[162:165], v208
	ds_read_b128 v[188:191], v209
	v_pk_fma_f32 v[172:173], v[68:69], v[144:145], v[140:141] op_sel_hi:[1,0,1]
	v_pk_fma_f32 v[174:175], v[70:71], v[144:145], v[142:143] op_sel_hi:[1,0,1]
	v_pk_fma_f32 v[176:177], v[76:77], v[144:145], v[136:137] op_sel_hi:[1,0,1]
	v_pk_fma_f32 v[178:179], v[78:79], v[144:145], v[138:139] op_sel_hi:[1,0,1]
	v_pk_fma_f32 v[180:181], v[120:121], v[144:145], v[132:133] op_sel_hi:[1,0,1]
	v_pk_fma_f32 v[182:183], v[122:123], v[144:145], v[134:135] op_sel_hi:[1,0,1]
	v_pk_fma_f32 v[184:185], v[124:125], v[144:145], v[128:129] op_sel_hi:[1,0,1]
	v_pk_fma_f32 v[186:187], v[126:127], v[144:145], v[130:131] op_sel_hi:[1,0,1]
	v_max_f32_e32 v172, 0, v172
	v_max_f32_e32 v173, 0, v173
	v_max_f32_e32 v174, 0, v174
	v_max_f32_e32 v175, 0, v175
	v_max_f32_e32 v176, 0, v176
	v_max_f32_e32 v177, 0, v177
	v_max_f32_e32 v178, 0, v178
	v_max_f32_e32 v179, 0, v179
	v_max_f32_e32 v180, 0, v180
	v_max_f32_e32 v181, 0, v181
	v_max_f32_e32 v182, 0, v182
	v_max_f32_e32 v183, 0, v183
	v_max_f32_e32 v184, 0, v184
	v_max_f32_e32 v185, 0, v185
	v_max_f32_e32 v186, 0, v186
	v_max_f32_e32 v187, 0, v187
	v_pk_mul_f32 v[172:173], v[172:173], v[172:173]
	v_pk_mul_f32 v[174:175], v[174:175], v[174:175]
	v_pk_mul_f32 v[176:177], v[176:177], v[176:177]
	v_pk_mul_f32 v[178:179], v[178:179], v[178:179]
	v_pk_mul_f32 v[180:181], v[180:181], v[180:181]
	v_pk_mul_f32 v[182:183], v[182:183], v[182:183]
	v_pk_mul_f32 v[184:185], v[184:185], v[184:185]
	v_pk_mul_f32 v[186:187], v[186:187], v[186:187]
	v_cvt_pk_bf16_f32 v172, v172, v173
	v_cvt_pk_bf16_f32 v180, v180, v181
	v_cvt_pk_bf16_f32 v173, v174, v175
	v_cvt_pk_bf16_f32 v181, v182, v183
	v_cvt_pk_bf16_f32 v174, v176, v177
	v_cvt_pk_bf16_f32 v182, v184, v185
	v_cvt_pk_bf16_f32 v175, v178, v179
	v_cvt_pk_bf16_f32 v183, v186, v187
	s_waitcnt lgkmcnt(0)
	global_store_dwordx4 v[212:213], v[162:165], off
	global_store_dwordx4 v[214:215], v[188:191], off
	s_mov_b64 s[100:101], 0x20000
	ds_write_b128 v207, v[172:175]
	ds_write_b128 v207, v[180:183] offset:256
	v_lshl_add_u64 v[212:213], v[212:213], 0, s[100:101]
	v_lshl_add_u64 v[214:215], v[214:215], 0, s[100:101]
	s_waitcnt lgkmcnt(0)
	s_barrier
	ds_read_b128 v[162:165], v210
	ds_read_b128 v[188:191], v211
	s_waitcnt lgkmcnt(0)
	global_store_dwordx4 v[212:213], v[162:165], off
	global_store_dwordx4 v[214:215], v[188:191], off

	.amdhsa_kernel _Z8yoco_fwd1P
		.amdhsa_group_segment_fixed_size 17392
		.amdhsa_private_segment_fixed_size 0
		.amdhsa_kernarg_size 480
		.amdhsa_user_sgpr_count 2
		.amdhsa_user_sgpr_dispatch_ptr 0
		.amdhsa_user_sgpr_queue_ptr 0
		.amdhsa_user_sgpr_kernarg_segment_ptr 1
		.amdhsa_user_sgpr_dispatch_id 0
		.amdhsa_user_sgpr_kernarg_preload_length 0
		.amdhsa_user_sgpr_kernarg_preload_offset 0
		.amdhsa_user_sgpr_private_segment_size 0
		.amdhsa_uses_dynamic_stack 0
		.amdhsa_enable_private_segment 0
		.amdhsa_system_sgpr_workgroup_id_x 1
		.amdhsa_system_sgpr_workgroup_id_y 0
		.amdhsa_system_sgpr_workgroup_id_z 0
		.amdhsa_system_sgpr_workgroup_info 0
		.amdhsa_system_vgpr_workitem_id 2
		.amdhsa_next_free_vgpr 256
		.amdhsa_next_free_sgpr 102
		.amdhsa_accum_offset 256
		.amdhsa_reserve_vcc 1
		.amdhsa_float_round_mode_32 0
		.amdhsa_float_round_mode_16_64 0
		.amdhsa_float_denorm_mode_32 3
		.amdhsa_float_denorm_mode_16_64 3
		.amdhsa_dx10_clamp 1
		.amdhsa_ieee_mode 1
		.amdhsa_fp16_overflow 0
		.amdhsa_tg_split 0
		.amdhsa_exception_fp_ieee_invalid_op 0
		.amdhsa_exception_fp_denorm_src 0
		.amdhsa_exception_fp_ieee_div_zero 0
		.amdhsa_exception_fp_ieee_overflow 0
		.amdhsa_exception_fp_ieee_underflow 0
		.amdhsa_exception_fp_ieee_inexact 0
		.amdhsa_exception_int_div_zero 0
	.end_amdhsa_kernel

amdhsa.kernels:
  - .agpr_count:     0
    .args:
      - .offset:         0
        .size:           224
        .value_kind:     by_value
      - .offset:         224
        .size:           4
        .value_kind:     hidden_block_count_x
      - .offset:         228
        .size:           4
        .value_kind:     hidden_block_count_y
      - .offset:         232
        .size:           4
        .value_kind:     hidden_block_count_z
      - .offset:         236
        .size:           2
        .value_kind:     hidden_group_size_x
      - .offset:         238
        .size:           2
        .value_kind:     hidden_group_size_y
      - .offset:         240
        .size:           2
        .value_kind:     hidden_group_size_z
      - .offset:         242
        .size:           2
        .value_kind:     hidden_remainder_x
      - .offset:         244
        .size:           2
        .value_kind:     hidden_remainder_y
      - .offset:         246
        .size:           2
        .value_kind:     hidden_remainder_z
      - .offset:         264
        .size:           8
        .value_kind:     hidden_global_offset_x
      - .offset:         272
        .size:           8
        .value_kind:     hidden_global_offset_y
      - .offset:         280
        .size:           8
        .value_kind:     hidden_global_offset_z
      - .offset:         288
        .size:           2
        .value_kind:     hidden_grid_dims
      - .offset:         312
        .size:           8
        .value_kind:     hidden_multigrid_sync_arg
      - .offset:         344
        .size:           4
        .value_kind:     hidden_dynamic_lds_size
    .group_segment_fixed_size: 17392
    .kernarg_segment_align: 8
    .kernarg_segment_size: 480
    .language:       OpenCL C
    .language_version:
      - 2
      - 0
    .max_flat_workgroup_size: 512
    .name:           _Z8yoco_fwd1P
    .private_segment_fixed_size: 0
    .sgpr_count:     108
    .sgpr_spill_count: 352
    .symbol:         _Z8yoco_fwd1P.kd
    .uniform_work_group_size: 1
    .uses_dynamic_stack: false
    .vgpr_count:     256
    .vgpr_spill_count: 0
    .wavefront_size: 64
